# v76 + remove redundant mid-block s_setprio 0/1 pairs in the four GEMM main loops (B,H,J,K)
# baseline (speedup 1.0000x reference)
.LBB0_308:
	s_add_u32 s28, s26, 0xfff80080
	s_addc_u32 s29, s27, -1
	s_add_i32 s65, 0, 0x10000
	s_cmp_eq_u32 s64, 28
	s_cselect_b32 s31, s21, s29
	s_cselect_b32 s30, s59, s28
	v_add_u32_e32 v178, s65, v168
	s_cselect_b32 s29, s60, s63
	s_cselect_b32 s28, s61, s62
	s_add_i32 s68, 0, 0x14000
	ds_read_b128 v[170:173], v178
	ds_read_b128 v[174:177], v178 offset:1024
	ds_read_b128 v[182:185], v178 offset:2048
	ds_read_b128 v[186:189], v178 offset:3072
	v_add_u32_e32 v178, s68, v168
	ds_read_b128 v[190:193], v178
	ds_read_b128 v[194:197], v178 offset:1024
	ds_read_b128 v[206:209], v178 offset:2048
	ds_read_b128 v[212:215], v178 offset:3072
	v_lshl_add_u64 v[178:179], s[26:27], 0, v[160:161]
	s_add_i32 m0, s48, 0xc000
	ds_read_b128 v[216:219], v169
	ds_read_b128 v[220:223], v169 offset:1024
	ds_read_b128 v[224:227], v169 offset:2048
	ds_read_b128 v[228:231], v169 offset:3072
	ds_read_b128 v[232:235], v169 offset:4096
	ds_read_b128 v[236:239], v169 offset:5120
	ds_read_b128 v[240:243], v169 offset:6144
	ds_read_b128 v[244:247], v169 offset:7168
	global_load_lds_dwordx4 v[178:179], off
	v_lshl_add_u64 v[178:179], s[26:27], 0, v[162:163]
	s_add_i32 m0, s48, 0xe000
	s_nop 0
	global_load_lds_dwordx4 v[178:179], off
	s_waitcnt vmcnt(8)
	s_waitcnt lgkmcnt(0)
	s_barrier
	s_setprio 1
	s_waitcnt lgkmcnt(0)
	v_mfma_f32_16x16x32_bf16 v[152:155], v[170:173], v[216:219], v[152:155]
	v_mfma_f32_16x16x32_bf16 v[148:151], v[182:185], v[216:219], v[148:151]
	v_mfma_f32_16x16x32_bf16 v[144:147], v[170:173], v[224:227], v[144:147]
	v_mfma_f32_16x16x32_bf16 v[140:143], v[182:185], v[224:227], v[140:143]
	v_mfma_f32_16x16x32_bf16 v[128:131], v[170:173], v[232:235], v[128:131]
	v_mfma_f32_16x16x32_bf16 v[124:127], v[182:185], v[232:235], v[124:127]
	v_mfma_f32_16x16x32_bf16 v[112:115], v[170:173], v[240:243], v[112:115]
	v_mfma_f32_16x16x32_bf16 v[108:111], v[182:185], v[240:243], v[108:111]
	v_mfma_f32_16x16x32_bf16 v[152:155], v[174:177], v[220:223], v[152:155]
	v_mfma_f32_16x16x32_bf16 v[148:151], v[186:189], v[220:223], v[148:151]
	v_mfma_f32_16x16x32_bf16 v[144:147], v[174:177], v[228:231], v[144:147]
	v_mfma_f32_16x16x32_bf16 v[140:143], v[186:189], v[228:231], v[140:143]
	v_mfma_f32_16x16x32_bf16 v[128:131], v[174:177], v[236:239], v[128:131]
	v_mfma_f32_16x16x32_bf16 v[124:127], v[186:189], v[236:239], v[124:127]
	v_mfma_f32_16x16x32_bf16 v[112:115], v[174:177], v[244:247], v[112:115]
	v_mfma_f32_16x16x32_bf16 v[108:111], v[186:189], v[244:247], v[108:111]
	v_mfma_f32_16x16x32_bf16 v[136:139], v[190:193], v[216:219], v[136:139]
	v_mfma_f32_16x16x32_bf16 v[132:135], v[206:209], v[216:219], v[132:135]
	v_mfma_f32_16x16x32_bf16 v[120:123], v[190:193], v[224:227], v[120:123]
	v_mfma_f32_16x16x32_bf16 v[116:119], v[206:209], v[224:227], v[116:119]
	v_mfma_f32_16x16x32_bf16 v[104:107], v[190:193], v[232:235], v[104:107]
	v_mfma_f32_16x16x32_bf16 v[100:103], v[206:209], v[232:235], v[100:103]
	v_mfma_f32_16x16x32_bf16 v[96:99], v[190:193], v[240:243], v[96:99]
	v_mfma_f32_16x16x32_bf16 v[92:95], v[206:209], v[240:243], v[92:95]
	v_mfma_f32_16x16x32_bf16 v[136:139], v[194:197], v[220:223], v[136:139]
	v_mfma_f32_16x16x32_bf16 v[132:135], v[212:215], v[220:223], v[132:135]
	v_mfma_f32_16x16x32_bf16 v[120:123], v[194:197], v[228:231], v[120:123]
	v_mfma_f32_16x16x32_bf16 v[116:119], v[212:215], v[228:231], v[116:119]
	v_mfma_f32_16x16x32_bf16 v[104:107], v[194:197], v[236:239], v[104:107]
	v_mfma_f32_16x16x32_bf16 v[100:103], v[212:215], v[236:239], v[100:103]
	v_mfma_f32_16x16x32_bf16 v[96:99], v[194:197], v[244:247], v[96:99]
	v_mfma_f32_16x16x32_bf16 v[92:95], v[212:215], v[244:247], v[92:95]
	s_setprio 0
	s_barrier
	s_add_i32 s65, s65, s47
	v_lshl_add_u64 v[178:179], s[28:29], 0, v[2:3]
	s_mov_b32 m0, s65
	ds_read_b128 v[216:219], v169 offset:16384
	ds_read_b128 v[220:223], v169 offset:17408
	ds_read_b128 v[224:227], v169 offset:18432
	ds_read_b128 v[228:231], v169 offset:19456
	ds_read_b128 v[232:235], v169 offset:20480
	ds_read_b128 v[236:239], v169 offset:21504
	ds_read_b128 v[240:243], v169 offset:22528
	ds_read_b128 v[244:247], v169 offset:23552
	global_load_lds_dwordx4 v[178:179], off
	s_add_i32 m0, s65, 0x2000
	s_add_u32 s66, s28, 0x80000
	v_lshl_add_u64 v[248:249], s[28:29], 0, v[158:159]
	s_addc_u32 s67, s29, 0
	s_add_i32 s65, s68, s47
	global_load_lds_dwordx4 v[248:249], off
	v_lshl_add_u64 v[250:251], s[66:67], 0, v[2:3]
	s_mov_b32 m0, s65
	v_lshl_add_u64 v[204:205], s[30:31], 0, v[156:157]
	global_load_lds_dwordx4 v[250:251], off
	v_lshl_add_u64 v[250:251], s[66:67], 0, v[158:159]
	s_add_i32 m0, s65, 0x2000
	s_nop 0
	global_load_lds_dwordx4 v[250:251], off
	v_lshl_add_u64 v[250:251], s[30:31], 0, v[0:1]
	s_mov_b32 m0, s48
	s_nop 0
	global_load_lds_dwordx4 v[250:251], off
	s_mov_b32 m0, s49
	s_nop 0
	global_load_lds_dwordx4 v[204:205], off
	s_waitcnt vmcnt(8)
	s_waitcnt lgkmcnt(0)
	s_barrier
	s_setprio 1
	s_waitcnt lgkmcnt(0)
	v_mfma_f32_16x16x32_bf16 v[88:91], v[170:173], v[216:219], v[88:91]
	v_mfma_f32_16x16x32_bf16 v[84:87], v[182:185], v[216:219], v[84:87]
	v_mfma_f32_16x16x32_bf16 v[80:83], v[170:173], v[224:227], v[80:83]
	v_mfma_f32_16x16x32_bf16 v[76:79], v[182:185], v[224:227], v[76:79]
	v_mfma_f32_16x16x32_bf16 v[64:67], v[170:173], v[232:235], v[64:67]
	v_mfma_f32_16x16x32_bf16 v[60:63], v[182:185], v[232:235], v[60:63]
	v_mfma_f32_16x16x32_bf16 v[48:51], v[170:173], v[240:243], v[48:51]
	v_mfma_f32_16x16x32_bf16 v[44:47], v[182:185], v[240:243], v[44:47]
	v_mfma_f32_16x16x32_bf16 v[88:91], v[174:177], v[220:223], v[88:91]
	v_mfma_f32_16x16x32_bf16 v[84:87], v[186:189], v[220:223], v[84:87]
	v_mfma_f32_16x16x32_bf16 v[80:83], v[174:177], v[228:231], v[80:83]
	v_mfma_f32_16x16x32_bf16 v[76:79], v[186:189], v[228:231], v[76:79]
	v_mfma_f32_16x16x32_bf16 v[64:67], v[174:177], v[236:239], v[64:67]
	v_mfma_f32_16x16x32_bf16 v[60:63], v[186:189], v[236:239], v[60:63]
	v_mfma_f32_16x16x32_bf16 v[48:51], v[174:177], v[244:247], v[48:51]
	v_mfma_f32_16x16x32_bf16 v[44:47], v[186:189], v[244:247], v[44:47]
	v_mfma_f32_16x16x32_bf16 v[72:75], v[190:193], v[216:219], v[72:75]
	v_mfma_f32_16x16x32_bf16 v[68:71], v[206:209], v[216:219], v[68:71]
	v_mfma_f32_16x16x32_bf16 v[56:59], v[190:193], v[224:227], v[56:59]
	v_mfma_f32_16x16x32_bf16 v[52:55], v[206:209], v[224:227], v[52:55]
	v_mfma_f32_16x16x32_bf16 v[40:43], v[190:193], v[232:235], v[40:43]
	v_mfma_f32_16x16x32_bf16 v[36:39], v[206:209], v[232:235], v[36:39]
	v_mfma_f32_16x16x32_bf16 v[32:35], v[190:193], v[240:243], v[32:35]
	v_mfma_f32_16x16x32_bf16 v[28:31], v[206:209], v[240:243], v[28:31]
	v_mfma_f32_16x16x32_bf16 v[72:75], v[194:197], v[220:223], v[72:75]
	v_mfma_f32_16x16x32_bf16 v[68:71], v[212:215], v[220:223], v[68:71]
	v_mfma_f32_16x16x32_bf16 v[56:59], v[194:197], v[228:231], v[56:59]
	v_mfma_f32_16x16x32_bf16 v[52:55], v[212:215], v[228:231], v[52:55]
	v_mfma_f32_16x16x32_bf16 v[40:43], v[194:197], v[236:239], v[40:43]
	v_mfma_f32_16x16x32_bf16 v[36:39], v[212:215], v[236:239], v[36:39]
	v_mfma_f32_16x16x32_bf16 v[32:35], v[194:197], v[244:247], v[32:35]
	v_mfma_f32_16x16x32_bf16 v[28:31], v[212:215], v[244:247], v[28:31]
	s_setprio 0
	s_barrier
	s_add_i32 s65, 0, 0x18000
	s_add_i32 s66, 0, 0x1c000
	v_add_u32_e32 v186, s65, v168
	v_add_u32_e32 v200, s66, v168
	ds_read_b128 v[170:173], v186
	ds_read_b128 v[174:177], v186 offset:1024
	ds_read_b128 v[182:185], v186 offset:2048
	ds_read_b128 v[186:189], v186 offset:3072
	ds_read_b128 v[190:193], v200
	ds_read_b128 v[194:197], v200 offset:1024
	ds_read_b128 v[206:209], v200 offset:2048
	ds_read_b128 v[212:215], v200 offset:3072
	s_add_u32 s30, s30, 0x80000
	s_addc_u32 s31, s31, 0
	s_mov_b32 m0, s50
	v_lshl_add_u64 v[200:201], s[30:31], 0, v[0:1]
	ds_read_b128 v[216:219], v169 offset:32768
	ds_read_b128 v[220:223], v169 offset:33792
	ds_read_b128 v[224:227], v169 offset:34816
	ds_read_b128 v[228:231], v169 offset:35840
	ds_read_b128 v[232:235], v169 offset:36864
	ds_read_b128 v[236:239], v169 offset:37888
	ds_read_b128 v[240:243], v169 offset:38912
	ds_read_b128 v[244:247], v169 offset:39936
	global_load_lds_dwordx4 v[200:201], off
	v_lshl_add_u64 v[200:201], s[30:31], 0, v[156:157]
	s_mov_b32 m0, s51
	s_nop 0
	global_load_lds_dwordx4 v[200:201], off
	s_waitcnt vmcnt(8)
	s_waitcnt lgkmcnt(0)
	s_barrier
	s_setprio 1
	s_waitcnt lgkmcnt(0)
	v_mfma_f32_16x16x32_bf16 v[152:155], v[170:173], v[216:219], v[152:155]
	v_mfma_f32_16x16x32_bf16 v[148:151], v[182:185], v[216:219], v[148:151]
	v_mfma_f32_16x16x32_bf16 v[144:147], v[170:173], v[224:227], v[144:147]
	v_mfma_f32_16x16x32_bf16 v[140:143], v[182:185], v[224:227], v[140:143]
	v_mfma_f32_16x16x32_bf16 v[128:131], v[170:173], v[232:235], v[128:131]
	v_mfma_f32_16x16x32_bf16 v[124:127], v[182:185], v[232:235], v[124:127]
	v_mfma_f32_16x16x32_bf16 v[112:115], v[170:173], v[240:243], v[112:115]
	v_mfma_f32_16x16x32_bf16 v[108:111], v[182:185], v[240:243], v[108:111]
	v_mfma_f32_16x16x32_bf16 v[152:155], v[174:177], v[220:223], v[152:155]
	v_mfma_f32_16x16x32_bf16 v[148:151], v[186:189], v[220:223], v[148:151]
	v_mfma_f32_16x16x32_bf16 v[144:147], v[174:177], v[228:231], v[144:147]
	v_mfma_f32_16x16x32_bf16 v[140:143], v[186:189], v[228:231], v[140:143]
	v_mfma_f32_16x16x32_bf16 v[128:131], v[174:177], v[236:239], v[128:131]
	v_mfma_f32_16x16x32_bf16 v[124:127], v[186:189], v[236:239], v[124:127]
	v_mfma_f32_16x16x32_bf16 v[112:115], v[174:177], v[244:247], v[112:115]
	v_mfma_f32_16x16x32_bf16 v[108:111], v[186:189], v[244:247], v[108:111]
	v_mfma_f32_16x16x32_bf16 v[136:139], v[190:193], v[216:219], v[136:139]
	v_mfma_f32_16x16x32_bf16 v[132:135], v[206:209], v[216:219], v[132:135]
	v_mfma_f32_16x16x32_bf16 v[120:123], v[190:193], v[224:227], v[120:123]
	v_mfma_f32_16x16x32_bf16 v[116:119], v[206:209], v[224:227], v[116:119]
	v_mfma_f32_16x16x32_bf16 v[104:107], v[190:193], v[232:235], v[104:107]
	v_mfma_f32_16x16x32_bf16 v[100:103], v[206:209], v[232:235], v[100:103]
	v_mfma_f32_16x16x32_bf16 v[96:99], v[190:193], v[240:243], v[96:99]
	v_mfma_f32_16x16x32_bf16 v[92:95], v[206:209], v[240:243], v[92:95]
	v_mfma_f32_16x16x32_bf16 v[136:139], v[194:197], v[220:223], v[136:139]
	v_mfma_f32_16x16x32_bf16 v[132:135], v[212:215], v[220:223], v[132:135]
	v_mfma_f32_16x16x32_bf16 v[120:123], v[194:197], v[228:231], v[120:123]
	v_mfma_f32_16x16x32_bf16 v[116:119], v[212:215], v[228:231], v[116:119]
	v_mfma_f32_16x16x32_bf16 v[104:107], v[194:197], v[236:239], v[104:107]
	v_mfma_f32_16x16x32_bf16 v[100:103], v[212:215], v[236:239], v[100:103]
	v_mfma_f32_16x16x32_bf16 v[96:99], v[194:197], v[244:247], v[96:99]
	v_mfma_f32_16x16x32_bf16 v[92:95], v[212:215], v[244:247], v[92:95]
	s_setprio 0
	s_barrier
	s_add_i32 s30, s65, s47
	v_lshl_add_u64 v[178:179], v[178:179], 0, s[10:11]
	s_mov_b32 m0, s30
	ds_read_b128 v[216:219], v169 offset:49152
	ds_read_b128 v[220:223], v169 offset:50176
	ds_read_b128 v[224:227], v169 offset:51200
	ds_read_b128 v[228:231], v169 offset:52224
	ds_read_b128 v[232:235], v169 offset:53248
	ds_read_b128 v[236:239], v169 offset:54272
	ds_read_b128 v[240:243], v169 offset:55296
	ds_read_b128 v[244:247], v169 offset:56320
	global_load_lds_dwordx4 v[178:179], off
	s_add_i32 m0, s30, 0x2000
	s_add_u32 s28, s28, 0x80080
	v_lshl_add_u64 v[178:179], v[248:249], 0, s[10:11]
	s_addc_u32 s29, s29, 0
	s_add_i32 s30, s66, s47
	global_load_lds_dwordx4 v[178:179], off
	v_lshl_add_u64 v[178:179], s[28:29], 0, v[2:3]
	s_mov_b32 m0, s30
	s_nop 0
	global_load_lds_dwordx4 v[178:179], off
	v_lshl_add_u64 v[178:179], s[28:29], 0, v[158:159]
	s_add_i32 m0, s30, 0x2000
	s_nop 0
	global_load_lds_dwordx4 v[178:179], off
	v_lshl_add_u64 v[178:179], v[250:251], 0, s[10:11]
	s_mov_b32 m0, s54
	s_nop 0
	global_load_lds_dwordx4 v[178:179], off
	v_lshl_add_u64 v[178:179], v[204:205], 0, s[10:11]
	s_mov_b32 m0, s55
	s_nop 0
	global_load_lds_dwordx4 v[178:179], off
	s_waitcnt vmcnt(8)
	s_waitcnt lgkmcnt(0)
	s_barrier
	s_setprio 1
	s_waitcnt lgkmcnt(0)
	v_mfma_f32_16x16x32_bf16 v[88:91], v[170:173], v[216:219], v[88:91]
	v_mfma_f32_16x16x32_bf16 v[84:87], v[182:185], v[216:219], v[84:87]
	v_mfma_f32_16x16x32_bf16 v[80:83], v[170:173], v[224:227], v[80:83]
	v_mfma_f32_16x16x32_bf16 v[76:79], v[182:185], v[224:227], v[76:79]
	v_mfma_f32_16x16x32_bf16 v[64:67], v[170:173], v[232:235], v[64:67]
	v_mfma_f32_16x16x32_bf16 v[60:63], v[182:185], v[232:235], v[60:63]
	v_mfma_f32_16x16x32_bf16 v[48:51], v[170:173], v[240:243], v[48:51]
	v_mfma_f32_16x16x32_bf16 v[44:47], v[182:185], v[240:243], v[44:47]
	v_mfma_f32_16x16x32_bf16 v[88:91], v[174:177], v[220:223], v[88:91]
	v_mfma_f32_16x16x32_bf16 v[84:87], v[186:189], v[220:223], v[84:87]
	v_mfma_f32_16x16x32_bf16 v[80:83], v[174:177], v[228:231], v[80:83]
	v_mfma_f32_16x16x32_bf16 v[76:79], v[186:189], v[228:231], v[76:79]
	v_mfma_f32_16x16x32_bf16 v[64:67], v[174:177], v[236:239], v[64:67]
	v_mfma_f32_16x16x32_bf16 v[60:63], v[186:189], v[236:239], v[60:63]
	v_mfma_f32_16x16x32_bf16 v[48:51], v[174:177], v[244:247], v[48:51]
	v_mfma_f32_16x16x32_bf16 v[44:47], v[186:189], v[244:247], v[44:47]
	v_mfma_f32_16x16x32_bf16 v[72:75], v[190:193], v[216:219], v[72:75]
	v_mfma_f32_16x16x32_bf16 v[68:71], v[206:209], v[216:219], v[68:71]
	v_mfma_f32_16x16x32_bf16 v[56:59], v[190:193], v[224:227], v[56:59]
	v_mfma_f32_16x16x32_bf16 v[52:55], v[206:209], v[224:227], v[52:55]
	v_mfma_f32_16x16x32_bf16 v[40:43], v[190:193], v[232:235], v[40:43]
	v_mfma_f32_16x16x32_bf16 v[36:39], v[206:209], v[232:235], v[36:39]
	v_mfma_f32_16x16x32_bf16 v[32:35], v[190:193], v[240:243], v[32:35]
	v_mfma_f32_16x16x32_bf16 v[28:31], v[206:209], v[240:243], v[28:31]
	v_mfma_f32_16x16x32_bf16 v[72:75], v[194:197], v[220:223], v[72:75]
	v_mfma_f32_16x16x32_bf16 v[68:71], v[212:215], v[220:223], v[68:71]
	v_mfma_f32_16x16x32_bf16 v[56:59], v[194:197], v[228:231], v[56:59]
	v_mfma_f32_16x16x32_bf16 v[52:55], v[212:215], v[228:231], v[52:55]
	v_mfma_f32_16x16x32_bf16 v[40:43], v[194:197], v[236:239], v[40:43]
	v_mfma_f32_16x16x32_bf16 v[36:39], v[212:215], v[236:239], v[36:39]
	v_mfma_f32_16x16x32_bf16 v[32:35], v[194:197], v[244:247], v[32:35]
	v_mfma_f32_16x16x32_bf16 v[28:31], v[212:215], v[244:247], v[28:31]
	s_setprio 0
	s_barrier
	s_add_i32 s64, s64, 2
	s_add_u32 s26, s26, 0x100
	s_addc_u32 s27, s27, 0
	s_add_u32 s62, s62, 0x100
	s_addc_u32 s63, s63, 0
	s_cmp_gt_u32 s64, 29
	s_cbranch_scc0 .LBB0_308
	s_and_b64 vcc, exec, s[16:17]
	s_cbranch_vccz .LBB0_311
	s_barrier

.LBB0_1334:
	s_add_i32 s51, s16, 2
	s_add_u32 s17, s12, 0xfff80080
	s_addc_u32 s18, s13, -1
	s_add_i32 s69, 0, 0x10000
	s_cmp_eq_u32 s9, s16
	s_cselect_b32 s19, s55, s18
	s_cselect_b32 s18, s54, s17
	s_cselect_b32 s17, s57, s21
	s_cselect_b32 s16, s56, s20
	s_add_i32 s72, 0, 0x14000
	v_add_u32_e32 v104, s69, v208
	v_add_u32_e32 v194, s72, v208
	ds_read_b128 v[84:87], v104
	ds_read_b128 v[88:91], v104 offset:1024
	ds_read_b128 v[100:103], v104 offset:2048
	ds_read_b128 v[104:107], v104 offset:3072
	ds_read_b128 v[172:175], v194
	ds_read_b128 v[176:179], v194 offset:1024
	ds_read_b128 v[190:193], v194 offset:2048
	ds_read_b128 v[194:197], v194 offset:3072
	v_lshl_add_u64 v[200:201], s[12:13], 0, v[186:187]
	s_add_i32 m0, s30, 0xc000
	ds_read_b128 v[212:215], v209
	ds_read_b128 v[216:219], v209 offset:1024
	ds_read_b128 v[220:223], v209 offset:2048
	ds_read_b128 v[224:227], v209 offset:3072
	ds_read_b128 v[228:231], v209 offset:4096
	ds_read_b128 v[232:235], v209 offset:5120
	ds_read_b128 v[236:239], v209 offset:6144
	ds_read_b128 v[240:243], v209 offset:7168
	global_load_lds_dwordx4 v[200:201], off
	v_lshl_add_u64 v[200:201], s[12:13], 0, v[188:189]
	s_add_i32 m0, s30, 0xe000
	s_nop 0
	global_load_lds_dwordx4 v[200:201], off
	s_waitcnt vmcnt(8)
	s_waitcnt lgkmcnt(0)
	s_barrier
	s_setprio 1
	s_waitcnt lgkmcnt(0)
	v_mfma_f32_16x16x32_bf16 v[168:171], v[84:87], v[212:215], v[168:171]
	v_mfma_f32_16x16x32_bf16 v[164:167], v[100:103], v[212:215], v[164:167]
	v_mfma_f32_16x16x32_bf16 v[152:155], v[84:87], v[220:223], v[152:155]
	v_mfma_f32_16x16x32_bf16 v[148:151], v[100:103], v[220:223], v[148:151]
	v_mfma_f32_16x16x32_bf16 v[136:139], v[84:87], v[228:231], v[136:139]
	v_mfma_f32_16x16x32_bf16 v[132:135], v[100:103], v[228:231], v[132:135]
	v_mfma_f32_16x16x32_bf16 v[120:123], v[84:87], v[236:239], v[120:123]
	v_mfma_f32_16x16x32_bf16 v[116:119], v[100:103], v[236:239], v[116:119]
	v_mfma_f32_16x16x32_bf16 v[168:171], v[88:91], v[216:219], v[168:171]
	v_mfma_f32_16x16x32_bf16 v[164:167], v[104:107], v[216:219], v[164:167]
	v_mfma_f32_16x16x32_bf16 v[152:155], v[88:91], v[224:227], v[152:155]
	v_mfma_f32_16x16x32_bf16 v[148:151], v[104:107], v[224:227], v[148:151]
	v_mfma_f32_16x16x32_bf16 v[136:139], v[88:91], v[232:235], v[136:139]
	v_mfma_f32_16x16x32_bf16 v[132:135], v[104:107], v[232:235], v[132:135]
	v_mfma_f32_16x16x32_bf16 v[120:123], v[88:91], v[240:243], v[120:123]
	v_mfma_f32_16x16x32_bf16 v[116:119], v[104:107], v[240:243], v[116:119]
	v_mfma_f32_16x16x32_bf16 v[160:163], v[172:175], v[212:215], v[160:163]
	v_mfma_f32_16x16x32_bf16 v[156:159], v[190:193], v[212:215], v[156:159]
	v_mfma_f32_16x16x32_bf16 v[144:147], v[172:175], v[220:223], v[144:147]
	v_mfma_f32_16x16x32_bf16 v[140:143], v[190:193], v[220:223], v[140:143]
	v_mfma_f32_16x16x32_bf16 v[128:131], v[172:175], v[228:231], v[128:131]
	v_mfma_f32_16x16x32_bf16 v[124:127], v[190:193], v[228:231], v[124:127]
	v_mfma_f32_16x16x32_bf16 v[112:115], v[172:175], v[236:239], v[112:115]
	v_mfma_f32_16x16x32_bf16 v[108:111], v[190:193], v[236:239], v[108:111]
	v_mfma_f32_16x16x32_bf16 v[160:163], v[176:179], v[216:219], v[160:163]
	v_mfma_f32_16x16x32_bf16 v[156:159], v[194:197], v[216:219], v[156:159]
	v_mfma_f32_16x16x32_bf16 v[144:147], v[176:179], v[224:227], v[144:147]
	v_mfma_f32_16x16x32_bf16 v[140:143], v[194:197], v[224:227], v[140:143]
	v_mfma_f32_16x16x32_bf16 v[128:131], v[176:179], v[232:235], v[128:131]
	v_mfma_f32_16x16x32_bf16 v[124:127], v[194:197], v[232:235], v[124:127]
	v_mfma_f32_16x16x32_bf16 v[112:115], v[176:179], v[240:243], v[112:115]
	v_mfma_f32_16x16x32_bf16 v[108:111], v[194:197], v[240:243], v[108:111]
	s_setprio 0
	s_barrier
	s_add_i32 s69, s69, s29
	v_lshl_add_u64 v[200:201], s[16:17], 0, v[2:3]
	s_mov_b32 m0, s69
	ds_read_b128 v[212:215], v209 offset:16384
	ds_read_b128 v[216:219], v209 offset:17408
	ds_read_b128 v[220:223], v209 offset:18432
	ds_read_b128 v[224:227], v209 offset:19456
	ds_read_b128 v[228:231], v209 offset:20480
	ds_read_b128 v[232:235], v209 offset:21504
	ds_read_b128 v[236:239], v209 offset:22528
	ds_read_b128 v[240:243], v209 offset:23552
	global_load_lds_dwordx4 v[200:201], off
	s_add_i32 m0, s69, 0x2000
	s_add_u32 s70, s16, 0x80000
	v_lshl_add_u64 v[204:205], s[16:17], 0, v[184:185]
	s_addc_u32 s71, s17, 0
	s_add_i32 s69, s72, s29
	global_load_lds_dwordx4 v[204:205], off
	v_lshl_add_u64 v[244:245], s[70:71], 0, v[2:3]
	s_mov_b32 m0, s69
	v_lshl_add_u64 v[246:247], s[18:19], 0, v[182:183]
	global_load_lds_dwordx4 v[244:245], off
	v_lshl_add_u64 v[244:245], s[70:71], 0, v[184:185]
	s_add_i32 m0, s69, 0x2000
	s_nop 0
	global_load_lds_dwordx4 v[244:245], off
	v_lshl_add_u64 v[244:245], s[18:19], 0, v[0:1]
	s_mov_b32 m0, s30
	s_nop 0
	global_load_lds_dwordx4 v[244:245], off
	s_mov_b32 m0, s31
	s_nop 0
	global_load_lds_dwordx4 v[246:247], off
	s_waitcnt vmcnt(8)
	s_waitcnt lgkmcnt(0)
	s_barrier
	s_setprio 1
	s_waitcnt lgkmcnt(0)
	v_mfma_f32_16x16x32_bf16 v[96:99], v[84:87], v[212:215], v[96:99]
	v_mfma_f32_16x16x32_bf16 v[92:95], v[100:103], v[212:215], v[92:95]
	v_mfma_f32_16x16x32_bf16 v[72:75], v[84:87], v[220:223], v[72:75]
	v_mfma_f32_16x16x32_bf16 v[68:71], v[100:103], v[220:223], v[68:71]
	v_mfma_f32_16x16x32_bf16 v[56:59], v[84:87], v[228:231], v[56:59]
	v_mfma_f32_16x16x32_bf16 v[52:55], v[100:103], v[228:231], v[52:55]
	v_mfma_f32_16x16x32_bf16 v[40:43], v[84:87], v[236:239], v[40:43]
	v_mfma_f32_16x16x32_bf16 v[36:39], v[100:103], v[236:239], v[36:39]
	v_mfma_f32_16x16x32_bf16 v[96:99], v[88:91], v[216:219], v[96:99]
	v_mfma_f32_16x16x32_bf16 v[92:95], v[104:107], v[216:219], v[92:95]
	v_mfma_f32_16x16x32_bf16 v[72:75], v[88:91], v[224:227], v[72:75]
	v_mfma_f32_16x16x32_bf16 v[68:71], v[104:107], v[224:227], v[68:71]
	v_mfma_f32_16x16x32_bf16 v[56:59], v[88:91], v[232:235], v[56:59]
	v_mfma_f32_16x16x32_bf16 v[52:55], v[104:107], v[232:235], v[52:55]
	v_mfma_f32_16x16x32_bf16 v[40:43], v[88:91], v[240:243], v[40:43]
	v_mfma_f32_16x16x32_bf16 v[36:39], v[104:107], v[240:243], v[36:39]
	v_mfma_f32_16x16x32_bf16 v[80:83], v[172:175], v[212:215], v[80:83]
	v_mfma_f32_16x16x32_bf16 v[76:79], v[190:193], v[212:215], v[76:79]
	v_mfma_f32_16x16x32_bf16 v[64:67], v[172:175], v[220:223], v[64:67]
	v_mfma_f32_16x16x32_bf16 v[60:63], v[190:193], v[220:223], v[60:63]
	v_mfma_f32_16x16x32_bf16 v[48:51], v[172:175], v[228:231], v[48:51]
	v_mfma_f32_16x16x32_bf16 v[44:47], v[190:193], v[228:231], v[44:47]
	v_mfma_f32_16x16x32_bf16 v[32:35], v[172:175], v[236:239], v[32:35]
	v_mfma_f32_16x16x32_bf16 v[28:31], v[190:193], v[236:239], v[28:31]
	v_mfma_f32_16x16x32_bf16 v[80:83], v[176:179], v[216:219], v[80:83]
	v_mfma_f32_16x16x32_bf16 v[76:79], v[194:197], v[216:219], v[76:79]
	v_mfma_f32_16x16x32_bf16 v[64:67], v[176:179], v[224:227], v[64:67]
	v_mfma_f32_16x16x32_bf16 v[60:63], v[194:197], v[224:227], v[60:63]
	v_mfma_f32_16x16x32_bf16 v[48:51], v[176:179], v[232:235], v[48:51]
	v_mfma_f32_16x16x32_bf16 v[44:47], v[194:197], v[232:235], v[44:47]
	v_mfma_f32_16x16x32_bf16 v[32:35], v[176:179], v[240:243], v[32:35]
	v_mfma_f32_16x16x32_bf16 v[28:31], v[194:197], v[240:243], v[28:31]
	s_setprio 0
	s_barrier
	s_add_i32 s69, 0, 0x18000
	s_add_i32 s70, 0, 0x1c000
	v_add_u32_e32 v104, s69, v208
	v_add_u32_e32 v194, s70, v208
	ds_read_b128 v[84:87], v104
	ds_read_b128 v[88:91], v104 offset:1024
	ds_read_b128 v[100:103], v104 offset:2048
	ds_read_b128 v[104:107], v104 offset:3072
	ds_read_b128 v[172:175], v194
	ds_read_b128 v[176:179], v194 offset:1024
	ds_read_b128 v[190:193], v194 offset:2048
	ds_read_b128 v[194:197], v194 offset:3072
	s_add_u32 s18, s18, 0x80000
	s_addc_u32 s19, s19, 0
	s_mov_b32 m0, s34
	v_lshl_add_u64 v[248:249], s[18:19], 0, v[0:1]
	ds_read_b128 v[212:215], v209 offset:32768
	ds_read_b128 v[216:219], v209 offset:33792
	ds_read_b128 v[220:223], v209 offset:34816
	ds_read_b128 v[224:227], v209 offset:35840
	ds_read_b128 v[228:231], v209 offset:36864
	ds_read_b128 v[232:235], v209 offset:37888
	ds_read_b128 v[236:239], v209 offset:38912
	ds_read_b128 v[240:243], v209 offset:39936
	global_load_lds_dwordx4 v[248:249], off
	v_lshl_add_u64 v[248:249], s[18:19], 0, v[182:183]
	s_mov_b32 m0, s35
	s_nop 0
	global_load_lds_dwordx4 v[248:249], off
	s_waitcnt vmcnt(8)
	s_waitcnt lgkmcnt(0)
	s_barrier
	s_setprio 1
	s_waitcnt lgkmcnt(0)
	v_mfma_f32_16x16x32_bf16 v[168:171], v[84:87], v[212:215], v[168:171]
	v_mfma_f32_16x16x32_bf16 v[164:167], v[100:103], v[212:215], v[164:167]
	v_mfma_f32_16x16x32_bf16 v[152:155], v[84:87], v[220:223], v[152:155]
	v_mfma_f32_16x16x32_bf16 v[148:151], v[100:103], v[220:223], v[148:151]
	v_mfma_f32_16x16x32_bf16 v[136:139], v[84:87], v[228:231], v[136:139]
	v_mfma_f32_16x16x32_bf16 v[132:135], v[100:103], v[228:231], v[132:135]
	v_mfma_f32_16x16x32_bf16 v[120:123], v[84:87], v[236:239], v[120:123]
	v_mfma_f32_16x16x32_bf16 v[116:119], v[100:103], v[236:239], v[116:119]
	v_mfma_f32_16x16x32_bf16 v[168:171], v[88:91], v[216:219], v[168:171]
	v_mfma_f32_16x16x32_bf16 v[164:167], v[104:107], v[216:219], v[164:167]
	v_mfma_f32_16x16x32_bf16 v[152:155], v[88:91], v[224:227], v[152:155]
	v_mfma_f32_16x16x32_bf16 v[148:151], v[104:107], v[224:227], v[148:151]
	v_mfma_f32_16x16x32_bf16 v[136:139], v[88:91], v[232:235], v[136:139]
	v_mfma_f32_16x16x32_bf16 v[132:135], v[104:107], v[232:235], v[132:135]
	v_mfma_f32_16x16x32_bf16 v[120:123], v[88:91], v[240:243], v[120:123]
	v_mfma_f32_16x16x32_bf16 v[116:119], v[104:107], v[240:243], v[116:119]
	v_mfma_f32_16x16x32_bf16 v[160:163], v[172:175], v[212:215], v[160:163]
	v_mfma_f32_16x16x32_bf16 v[156:159], v[190:193], v[212:215], v[156:159]
	v_mfma_f32_16x16x32_bf16 v[144:147], v[172:175], v[220:223], v[144:147]
	v_mfma_f32_16x16x32_bf16 v[140:143], v[190:193], v[220:223], v[140:143]
	v_mfma_f32_16x16x32_bf16 v[128:131], v[172:175], v[228:231], v[128:131]
	v_mfma_f32_16x16x32_bf16 v[124:127], v[190:193], v[228:231], v[124:127]
	v_mfma_f32_16x16x32_bf16 v[112:115], v[172:175], v[236:239], v[112:115]
	v_mfma_f32_16x16x32_bf16 v[108:111], v[190:193], v[236:239], v[108:111]
	v_mfma_f32_16x16x32_bf16 v[160:163], v[176:179], v[216:219], v[160:163]
	v_mfma_f32_16x16x32_bf16 v[156:159], v[194:197], v[216:219], v[156:159]
	v_mfma_f32_16x16x32_bf16 v[144:147], v[176:179], v[224:227], v[144:147]
	v_mfma_f32_16x16x32_bf16 v[140:143], v[194:197], v[224:227], v[140:143]
	v_mfma_f32_16x16x32_bf16 v[128:131], v[176:179], v[232:235], v[128:131]
	v_mfma_f32_16x16x32_bf16 v[124:127], v[194:197], v[232:235], v[124:127]
	v_mfma_f32_16x16x32_bf16 v[112:115], v[176:179], v[240:243], v[112:115]
	v_mfma_f32_16x16x32_bf16 v[108:111], v[194:197], v[240:243], v[108:111]
	s_setprio 0
	s_barrier
	s_add_i32 s18, s69, s29
	v_lshl_add_u64 v[200:201], v[200:201], 0, s[10:11]
	s_mov_b32 m0, s18
	ds_read_b128 v[212:215], v209 offset:49152
	ds_read_b128 v[216:219], v209 offset:50176
	ds_read_b128 v[220:223], v209 offset:51200
	ds_read_b128 v[224:227], v209 offset:52224
	ds_read_b128 v[228:231], v209 offset:53248
	ds_read_b128 v[232:235], v209 offset:54272
	ds_read_b128 v[236:239], v209 offset:55296
	ds_read_b128 v[240:243], v209 offset:56320
	global_load_lds_dwordx4 v[200:201], off
	s_add_i32 m0, s18, 0x2000
	s_add_u32 s16, s16, 0x80080
	v_lshl_add_u64 v[200:201], v[204:205], 0, s[10:11]
	s_addc_u32 s17, s17, 0
	s_add_i32 s18, s70, s29
	global_load_lds_dwordx4 v[200:201], off
	v_lshl_add_u64 v[200:201], s[16:17], 0, v[2:3]
	s_mov_b32 m0, s18
	s_nop 0
	global_load_lds_dwordx4 v[200:201], off
	v_lshl_add_u64 v[200:201], s[16:17], 0, v[184:185]
	s_add_i32 m0, s18, 0x2000
	s_nop 0
	global_load_lds_dwordx4 v[200:201], off
	v_lshl_add_u64 v[200:201], v[244:245], 0, s[10:11]
	s_mov_b32 m0, s62
	s_nop 0
	global_load_lds_dwordx4 v[200:201], off
	v_lshl_add_u64 v[200:201], v[246:247], 0, s[10:11]
	s_mov_b32 m0, s63
	s_nop 0
	global_load_lds_dwordx4 v[200:201], off
	s_waitcnt vmcnt(8)
	s_waitcnt lgkmcnt(0)
	s_barrier
	s_setprio 1
	s_waitcnt lgkmcnt(0)
	v_mfma_f32_16x16x32_bf16 v[96:99], v[84:87], v[212:215], v[96:99]
	v_mfma_f32_16x16x32_bf16 v[92:95], v[100:103], v[212:215], v[92:95]
	v_mfma_f32_16x16x32_bf16 v[72:75], v[84:87], v[220:223], v[72:75]
	v_mfma_f32_16x16x32_bf16 v[68:71], v[100:103], v[220:223], v[68:71]
	v_mfma_f32_16x16x32_bf16 v[56:59], v[84:87], v[228:231], v[56:59]
	v_mfma_f32_16x16x32_bf16 v[52:55], v[100:103], v[228:231], v[52:55]
	v_mfma_f32_16x16x32_bf16 v[40:43], v[84:87], v[236:239], v[40:43]
	v_mfma_f32_16x16x32_bf16 v[36:39], v[100:103], v[236:239], v[36:39]
	v_mfma_f32_16x16x32_bf16 v[96:99], v[88:91], v[216:219], v[96:99]
	v_mfma_f32_16x16x32_bf16 v[92:95], v[104:107], v[216:219], v[92:95]
	v_mfma_f32_16x16x32_bf16 v[72:75], v[88:91], v[224:227], v[72:75]
	v_mfma_f32_16x16x32_bf16 v[68:71], v[104:107], v[224:227], v[68:71]
	v_mfma_f32_16x16x32_bf16 v[56:59], v[88:91], v[232:235], v[56:59]
	v_mfma_f32_16x16x32_bf16 v[52:55], v[104:107], v[232:235], v[52:55]
	v_mfma_f32_16x16x32_bf16 v[40:43], v[88:91], v[240:243], v[40:43]
	v_mfma_f32_16x16x32_bf16 v[36:39], v[104:107], v[240:243], v[36:39]
	v_mfma_f32_16x16x32_bf16 v[80:83], v[172:175], v[212:215], v[80:83]
	v_mfma_f32_16x16x32_bf16 v[76:79], v[190:193], v[212:215], v[76:79]
	v_mfma_f32_16x16x32_bf16 v[64:67], v[172:175], v[220:223], v[64:67]
	v_mfma_f32_16x16x32_bf16 v[60:63], v[190:193], v[220:223], v[60:63]
	v_mfma_f32_16x16x32_bf16 v[48:51], v[172:175], v[228:231], v[48:51]
	v_mfma_f32_16x16x32_bf16 v[44:47], v[190:193], v[228:231], v[44:47]
	v_mfma_f32_16x16x32_bf16 v[32:35], v[172:175], v[236:239], v[32:35]
	v_mfma_f32_16x16x32_bf16 v[28:31], v[190:193], v[236:239], v[28:31]
	v_mfma_f32_16x16x32_bf16 v[80:83], v[176:179], v[216:219], v[80:83]
	v_mfma_f32_16x16x32_bf16 v[76:79], v[194:197], v[216:219], v[76:79]
	v_mfma_f32_16x16x32_bf16 v[64:67], v[176:179], v[224:227], v[64:67]
	v_mfma_f32_16x16x32_bf16 v[60:63], v[194:197], v[224:227], v[60:63]
	v_mfma_f32_16x16x32_bf16 v[48:51], v[176:179], v[232:235], v[48:51]
	v_mfma_f32_16x16x32_bf16 v[44:47], v[194:197], v[232:235], v[44:47]
	v_mfma_f32_16x16x32_bf16 v[32:35], v[176:179], v[240:243], v[32:35]
	v_mfma_f32_16x16x32_bf16 v[28:31], v[194:197], v[240:243], v[28:31]
	s_setprio 0
	s_barrier
	s_add_u32 s12, s12, 0x100
	s_addc_u32 s13, s13, 0
	s_add_u32 s20, s20, 0x100
	s_addc_u32 s21, s21, 0
	s_cmp_ge_u32 s51, s39
	s_mov_b32 s16, s51
	s_cbranch_scc0 .LBB0_1334
	s_and_b64 vcc, exec, s[46:47]
	s_cbranch_vccz .LBB0_1337
	s_barrier

.LBB0_1580:
	s_add_u32 s16, s12, 0xfff80080
	s_addc_u32 s17, s13, -1
	s_add_i32 s70, 0, 0x10000
	s_cmp_eq_u32 s69, 28
	s_cselect_b32 s19, s53, s17
	s_cselect_b32 s18, s64, s16
	s_cselect_b32 s17, s65, s68
	s_cselect_b32 s16, s66, s67
	s_add_i32 s72, 0, 0x14000
	v_lshl_add_u64 v[200:201], s[12:13], 0, v[160:161]
	s_add_i32 m0, s34, 0xc000
	s_nop 0
	global_load_lds_dwordx4 v[200:201], off
	v_lshl_add_u64 v[204:205], s[12:13], 0, v[162:163]
	s_add_i32 m0, s34, 0xe000
	s_nop 0
	global_load_lds_dwordx4 v[204:205], off
	v_add_u32_e32 v164, s70, v170
	ds_read_b128 v[172:175], v164
	ds_read_b128 v[176:179], v164 offset:1024
	ds_read_b128 v[182:185], v164 offset:2048
	ds_read_b128 v[186:189], v164 offset:3072
	v_add_u32_e32 v164, s72, v170
	ds_read_b128 v[190:193], v164
	ds_read_b128 v[194:197], v164 offset:1024
	ds_read_b128 v[206:209], v164 offset:2048
	ds_read_b128 v[212:215], v164 offset:3072
	ds_read_b128 v[216:219], v171
	ds_read_b128 v[220:223], v171 offset:1024
	ds_read_b128 v[224:227], v171 offset:2048
	ds_read_b128 v[228:231], v171 offset:3072
	ds_read_b128 v[232:235], v171 offset:4096
	ds_read_b128 v[236:239], v171 offset:5120
	ds_read_b128 v[240:243], v171 offset:6144
	ds_read_b128 v[244:247], v171 offset:7168
	s_waitcnt vmcnt(8)
	s_waitcnt lgkmcnt(0)
	s_barrier
	s_setprio 1
	s_waitcnt lgkmcnt(0)
	v_mfma_f32_16x16x32_bf16 v[152:155], v[172:175], v[216:219], v[152:155]
	v_mfma_f32_16x16x32_bf16 v[144:147], v[182:185], v[216:219], v[144:147]
	v_mfma_f32_16x16x32_bf16 v[136:139], v[172:175], v[224:227], v[136:139]
	v_mfma_f32_16x16x32_bf16 v[128:131], v[182:185], v[224:227], v[128:131]
	v_mfma_f32_16x16x32_bf16 v[120:123], v[172:175], v[232:235], v[120:123]
	v_mfma_f32_16x16x32_bf16 v[112:115], v[182:185], v[232:235], v[112:115]
	v_mfma_f32_16x16x32_bf16 v[104:107], v[172:175], v[240:243], v[104:107]
	v_mfma_f32_16x16x32_bf16 v[96:99], v[182:185], v[240:243], v[96:99]
	v_mfma_f32_16x16x32_bf16 v[152:155], v[176:179], v[220:223], v[152:155]
	v_mfma_f32_16x16x32_bf16 v[144:147], v[186:189], v[220:223], v[144:147]
	v_mfma_f32_16x16x32_bf16 v[136:139], v[176:179], v[228:231], v[136:139]
	v_mfma_f32_16x16x32_bf16 v[128:131], v[186:189], v[228:231], v[128:131]
	v_mfma_f32_16x16x32_bf16 v[120:123], v[176:179], v[236:239], v[120:123]
	v_mfma_f32_16x16x32_bf16 v[112:115], v[186:189], v[236:239], v[112:115]
	v_mfma_f32_16x16x32_bf16 v[104:107], v[176:179], v[244:247], v[104:107]
	v_mfma_f32_16x16x32_bf16 v[96:99], v[186:189], v[244:247], v[96:99]
	v_mfma_f32_16x16x32_bf16 v[148:151], v[190:193], v[216:219], v[148:151]
	v_mfma_f32_16x16x32_bf16 v[140:143], v[206:209], v[216:219], v[140:143]
	v_mfma_f32_16x16x32_bf16 v[132:135], v[190:193], v[224:227], v[132:135]
	v_mfma_f32_16x16x32_bf16 v[124:127], v[206:209], v[224:227], v[124:127]
	v_mfma_f32_16x16x32_bf16 v[116:119], v[190:193], v[232:235], v[116:119]
	v_mfma_f32_16x16x32_bf16 v[108:111], v[206:209], v[232:235], v[108:111]
	v_mfma_f32_16x16x32_bf16 v[100:103], v[190:193], v[240:243], v[100:103]
	v_mfma_f32_16x16x32_bf16 v[92:95], v[206:209], v[240:243], v[92:95]
	v_mfma_f32_16x16x32_bf16 v[148:151], v[194:197], v[220:223], v[148:151]
	v_mfma_f32_16x16x32_bf16 v[140:143], v[212:215], v[220:223], v[140:143]
	v_mfma_f32_16x16x32_bf16 v[132:135], v[194:197], v[228:231], v[132:135]
	v_mfma_f32_16x16x32_bf16 v[124:127], v[212:215], v[228:231], v[124:127]
	v_mfma_f32_16x16x32_bf16 v[116:119], v[194:197], v[236:239], v[116:119]
	v_mfma_f32_16x16x32_bf16 v[108:111], v[212:215], v[236:239], v[108:111]
	v_mfma_f32_16x16x32_bf16 v[100:103], v[194:197], v[244:247], v[100:103]
	v_mfma_f32_16x16x32_bf16 v[92:95], v[212:215], v[244:247], v[92:95]
	s_setprio 0
	s_barrier
	s_add_i32 s70, s70, s28
	v_lshl_add_u64 v[164:165], s[16:17], 0, v[2:3]
	s_mov_b32 m0, s70
	s_nop 0
	global_load_lds_dwordx4 v[164:165], off
	s_add_i32 m0, s70, 0x2000
	s_add_u32 s70, s16, 0x80000
	v_lshl_add_u64 v[200:201], s[16:17], 0, v[0:1]
	s_addc_u32 s71, s17, 0
	s_add_i32 s72, s72, s28
	global_load_lds_dwordx4 v[200:201], off
	v_lshl_add_u64 v[204:205], s[70:71], 0, v[2:3]
	s_mov_b32 m0, s72
	v_lshl_add_u64 v[248:249], s[18:19], 0, v[156:157]
	global_load_lds_dwordx4 v[204:205], off
	v_lshl_add_u64 v[204:205], s[70:71], 0, v[0:1]
	s_add_i32 m0, s72, 0x2000
	s_nop 0
	global_load_lds_dwordx4 v[204:205], off
	v_lshl_add_u64 v[204:205], s[18:19], 0, v[158:159]
	s_mov_b32 m0, s34
	s_nop 0
	global_load_lds_dwordx4 v[204:205], off
	s_mov_b32 m0, s35
	s_nop 0
	global_load_lds_dwordx4 v[248:249], off
	ds_read_b128 v[216:219], v171 offset:16384
	ds_read_b128 v[220:223], v171 offset:17408
	ds_read_b128 v[224:227], v171 offset:18432
	ds_read_b128 v[228:231], v171 offset:19456
	ds_read_b128 v[232:235], v171 offset:20480
	ds_read_b128 v[236:239], v171 offset:21504
	ds_read_b128 v[240:243], v171 offset:22528
	ds_read_b128 v[244:247], v171 offset:23552
	s_waitcnt vmcnt(8)
	s_waitcnt lgkmcnt(0)
	s_barrier
	s_setprio 1
	s_waitcnt lgkmcnt(0)
	v_mfma_f32_16x16x32_bf16 v[88:91], v[172:175], v[216:219], v[88:91]
	v_mfma_f32_16x16x32_bf16 v[80:83], v[182:185], v[216:219], v[80:83]
	v_mfma_f32_16x16x32_bf16 v[72:75], v[172:175], v[224:227], v[72:75]
	v_mfma_f32_16x16x32_bf16 v[64:67], v[182:185], v[224:227], v[64:67]
	v_mfma_f32_16x16x32_bf16 v[56:59], v[172:175], v[232:235], v[56:59]
	v_mfma_f32_16x16x32_bf16 v[48:51], v[182:185], v[232:235], v[48:51]
	v_mfma_f32_16x16x32_bf16 v[40:43], v[172:175], v[240:243], v[40:43]
	v_mfma_f32_16x16x32_bf16 v[32:35], v[182:185], v[240:243], v[32:35]
	v_mfma_f32_16x16x32_bf16 v[88:91], v[176:179], v[220:223], v[88:91]
	v_mfma_f32_16x16x32_bf16 v[80:83], v[186:189], v[220:223], v[80:83]
	v_mfma_f32_16x16x32_bf16 v[72:75], v[176:179], v[228:231], v[72:75]
	v_mfma_f32_16x16x32_bf16 v[64:67], v[186:189], v[228:231], v[64:67]
	v_mfma_f32_16x16x32_bf16 v[56:59], v[176:179], v[236:239], v[56:59]
	v_mfma_f32_16x16x32_bf16 v[48:51], v[186:189], v[236:239], v[48:51]
	v_mfma_f32_16x16x32_bf16 v[40:43], v[176:179], v[244:247], v[40:43]
	v_mfma_f32_16x16x32_bf16 v[32:35], v[186:189], v[244:247], v[32:35]
	v_mfma_f32_16x16x32_bf16 v[84:87], v[190:193], v[216:219], v[84:87]
	v_mfma_f32_16x16x32_bf16 v[76:79], v[206:209], v[216:219], v[76:79]
	v_mfma_f32_16x16x32_bf16 v[68:71], v[190:193], v[224:227], v[68:71]
	v_mfma_f32_16x16x32_bf16 v[60:63], v[206:209], v[224:227], v[60:63]
	v_mfma_f32_16x16x32_bf16 v[52:55], v[190:193], v[232:235], v[52:55]
	v_mfma_f32_16x16x32_bf16 v[44:47], v[206:209], v[232:235], v[44:47]
	v_mfma_f32_16x16x32_bf16 v[36:39], v[190:193], v[240:243], v[36:39]
	v_mfma_f32_16x16x32_bf16 v[28:31], v[206:209], v[240:243], v[28:31]
	v_mfma_f32_16x16x32_bf16 v[84:87], v[194:197], v[220:223], v[84:87]
	v_mfma_f32_16x16x32_bf16 v[76:79], v[212:215], v[220:223], v[76:79]
	v_mfma_f32_16x16x32_bf16 v[68:71], v[194:197], v[228:231], v[68:71]
	v_mfma_f32_16x16x32_bf16 v[60:63], v[212:215], v[228:231], v[60:63]
	v_mfma_f32_16x16x32_bf16 v[52:55], v[194:197], v[236:239], v[52:55]
	v_mfma_f32_16x16x32_bf16 v[44:47], v[212:215], v[236:239], v[44:47]
	v_mfma_f32_16x16x32_bf16 v[36:39], v[194:197], v[244:247], v[36:39]
	v_mfma_f32_16x16x32_bf16 v[28:31], v[212:215], v[244:247], v[28:31]
	s_setprio 0
	s_barrier
	s_add_i32 s70, 0, 0x18000
	s_add_i32 s71, 0, 0x1c000
	s_add_u32 s18, s18, 0x80000
	s_addc_u32 s19, s19, 0
	s_mov_b32 m0, s36
	v_lshl_add_u64 v[250:251], s[18:19], 0, v[158:159]
	global_load_lds_dwordx4 v[250:251], off
	v_lshl_add_u64 v[250:251], s[18:19], 0, v[156:157]
	s_mov_b32 m0, s37
	s_nop 0
	global_load_lds_dwordx4 v[250:251], off
	v_add_u32_e32 v186, s70, v170
	v_add_u32_e32 v212, s71, v170
	ds_read_b128 v[172:175], v186
	ds_read_b128 v[176:179], v186 offset:1024
	ds_read_b128 v[182:185], v186 offset:2048
	ds_read_b128 v[186:189], v186 offset:3072
	ds_read_b128 v[190:193], v212
	ds_read_b128 v[194:197], v212 offset:1024
	ds_read_b128 v[206:209], v212 offset:2048
	ds_read_b128 v[212:215], v212 offset:3072
	ds_read_b128 v[216:219], v171 offset:32768
	ds_read_b128 v[220:223], v171 offset:33792
	ds_read_b128 v[224:227], v171 offset:34816
	ds_read_b128 v[228:231], v171 offset:35840
	ds_read_b128 v[232:235], v171 offset:36864
	ds_read_b128 v[236:239], v171 offset:37888
	ds_read_b128 v[240:243], v171 offset:38912
	ds_read_b128 v[244:247], v171 offset:39936
	s_waitcnt vmcnt(8)
	s_waitcnt lgkmcnt(0)
	s_barrier
	s_setprio 1
	s_waitcnt lgkmcnt(0)
	v_mfma_f32_16x16x32_bf16 v[152:155], v[172:175], v[216:219], v[152:155]
	v_mfma_f32_16x16x32_bf16 v[144:147], v[182:185], v[216:219], v[144:147]
	v_mfma_f32_16x16x32_bf16 v[136:139], v[172:175], v[224:227], v[136:139]
	v_mfma_f32_16x16x32_bf16 v[128:131], v[182:185], v[224:227], v[128:131]
	v_mfma_f32_16x16x32_bf16 v[120:123], v[172:175], v[232:235], v[120:123]
	v_mfma_f32_16x16x32_bf16 v[112:115], v[182:185], v[232:235], v[112:115]
	v_mfma_f32_16x16x32_bf16 v[104:107], v[172:175], v[240:243], v[104:107]
	v_mfma_f32_16x16x32_bf16 v[96:99], v[182:185], v[240:243], v[96:99]
	v_mfma_f32_16x16x32_bf16 v[152:155], v[176:179], v[220:223], v[152:155]
	v_mfma_f32_16x16x32_bf16 v[144:147], v[186:189], v[220:223], v[144:147]
	v_mfma_f32_16x16x32_bf16 v[136:139], v[176:179], v[228:231], v[136:139]
	v_mfma_f32_16x16x32_bf16 v[128:131], v[186:189], v[228:231], v[128:131]
	v_mfma_f32_16x16x32_bf16 v[120:123], v[176:179], v[236:239], v[120:123]
	v_mfma_f32_16x16x32_bf16 v[112:115], v[186:189], v[236:239], v[112:115]
	v_mfma_f32_16x16x32_bf16 v[104:107], v[176:179], v[244:247], v[104:107]
	v_mfma_f32_16x16x32_bf16 v[96:99], v[186:189], v[244:247], v[96:99]
	v_mfma_f32_16x16x32_bf16 v[148:151], v[190:193], v[216:219], v[148:151]
	v_mfma_f32_16x16x32_bf16 v[140:143], v[206:209], v[216:219], v[140:143]
	v_mfma_f32_16x16x32_bf16 v[132:135], v[190:193], v[224:227], v[132:135]
	v_mfma_f32_16x16x32_bf16 v[124:127], v[206:209], v[224:227], v[124:127]
	v_mfma_f32_16x16x32_bf16 v[116:119], v[190:193], v[232:235], v[116:119]
	v_mfma_f32_16x16x32_bf16 v[108:111], v[206:209], v[232:235], v[108:111]
	v_mfma_f32_16x16x32_bf16 v[100:103], v[190:193], v[240:243], v[100:103]
	v_mfma_f32_16x16x32_bf16 v[92:95], v[206:209], v[240:243], v[92:95]
	v_mfma_f32_16x16x32_bf16 v[148:151], v[194:197], v[220:223], v[148:151]
	v_mfma_f32_16x16x32_bf16 v[140:143], v[212:215], v[220:223], v[140:143]
	v_mfma_f32_16x16x32_bf16 v[132:135], v[194:197], v[228:231], v[132:135]
	v_mfma_f32_16x16x32_bf16 v[124:127], v[212:215], v[228:231], v[124:127]
	v_mfma_f32_16x16x32_bf16 v[116:119], v[194:197], v[236:239], v[116:119]
	v_mfma_f32_16x16x32_bf16 v[108:111], v[212:215], v[236:239], v[108:111]
	v_mfma_f32_16x16x32_bf16 v[100:103], v[194:197], v[244:247], v[100:103]
	v_mfma_f32_16x16x32_bf16 v[92:95], v[212:215], v[244:247], v[92:95]
	s_setprio 0
	s_barrier
	s_add_i32 s18, s70, s28
	v_lshl_add_u64 v[164:165], v[164:165], 0, s[10:11]
	s_mov_b32 m0, s18
	s_nop 0
	global_load_lds_dwordx4 v[164:165], off
	s_add_i32 m0, s18, 0x2000
	s_add_u32 s16, s16, 0x80080
	v_lshl_add_u64 v[164:165], v[200:201], 0, s[10:11]
	s_addc_u32 s17, s17, 0
	s_add_i32 s18, s71, s28
	global_load_lds_dwordx4 v[164:165], off
	v_lshl_add_u64 v[164:165], s[16:17], 0, v[2:3]
	s_mov_b32 m0, s18
	s_nop 0
	global_load_lds_dwordx4 v[164:165], off
	v_lshl_add_u64 v[164:165], s[16:17], 0, v[0:1]
	s_add_i32 m0, s18, 0x2000
	s_nop 0
	global_load_lds_dwordx4 v[164:165], off
	v_lshl_add_u64 v[164:165], v[204:205], 0, s[10:11]
	s_mov_b32 m0, s59
	s_nop 0
	global_load_lds_dwordx4 v[164:165], off
	v_lshl_add_u64 v[164:165], v[248:249], 0, s[10:11]
	s_mov_b32 m0, s60
	s_nop 0
	global_load_lds_dwordx4 v[164:165], off
	ds_read_b128 v[216:219], v171 offset:49152
	ds_read_b128 v[220:223], v171 offset:50176
	ds_read_b128 v[224:227], v171 offset:51200
	ds_read_b128 v[228:231], v171 offset:52224
	ds_read_b128 v[232:235], v171 offset:53248
	ds_read_b128 v[236:239], v171 offset:54272
	ds_read_b128 v[240:243], v171 offset:55296
	ds_read_b128 v[244:247], v171 offset:56320
	s_waitcnt vmcnt(8)
	s_waitcnt lgkmcnt(0)
	s_barrier
	s_setprio 1
	s_waitcnt lgkmcnt(0)
	v_mfma_f32_16x16x32_bf16 v[88:91], v[172:175], v[216:219], v[88:91]
	v_mfma_f32_16x16x32_bf16 v[80:83], v[182:185], v[216:219], v[80:83]
	v_mfma_f32_16x16x32_bf16 v[72:75], v[172:175], v[224:227], v[72:75]
	v_mfma_f32_16x16x32_bf16 v[64:67], v[182:185], v[224:227], v[64:67]
	v_mfma_f32_16x16x32_bf16 v[56:59], v[172:175], v[232:235], v[56:59]
	v_mfma_f32_16x16x32_bf16 v[48:51], v[182:185], v[232:235], v[48:51]
	v_mfma_f32_16x16x32_bf16 v[40:43], v[172:175], v[240:243], v[40:43]
	v_mfma_f32_16x16x32_bf16 v[32:35], v[182:185], v[240:243], v[32:35]
	v_mfma_f32_16x16x32_bf16 v[88:91], v[176:179], v[220:223], v[88:91]
	v_mfma_f32_16x16x32_bf16 v[80:83], v[186:189], v[220:223], v[80:83]
	v_mfma_f32_16x16x32_bf16 v[72:75], v[176:179], v[228:231], v[72:75]
	v_mfma_f32_16x16x32_bf16 v[64:67], v[186:189], v[228:231], v[64:67]
	v_mfma_f32_16x16x32_bf16 v[56:59], v[176:179], v[236:239], v[56:59]
	v_mfma_f32_16x16x32_bf16 v[48:51], v[186:189], v[236:239], v[48:51]
	v_mfma_f32_16x16x32_bf16 v[40:43], v[176:179], v[244:247], v[40:43]
	v_mfma_f32_16x16x32_bf16 v[32:35], v[186:189], v[244:247], v[32:35]
	v_mfma_f32_16x16x32_bf16 v[84:87], v[190:193], v[216:219], v[84:87]
	v_mfma_f32_16x16x32_bf16 v[76:79], v[206:209], v[216:219], v[76:79]
	v_mfma_f32_16x16x32_bf16 v[68:71], v[190:193], v[224:227], v[68:71]
	v_mfma_f32_16x16x32_bf16 v[60:63], v[206:209], v[224:227], v[60:63]
	v_mfma_f32_16x16x32_bf16 v[52:55], v[190:193], v[232:235], v[52:55]
	v_mfma_f32_16x16x32_bf16 v[44:47], v[206:209], v[232:235], v[44:47]
	v_mfma_f32_16x16x32_bf16 v[36:39], v[190:193], v[240:243], v[36:39]
	v_mfma_f32_16x16x32_bf16 v[28:31], v[206:209], v[240:243], v[28:31]
	v_mfma_f32_16x16x32_bf16 v[84:87], v[194:197], v[220:223], v[84:87]
	v_mfma_f32_16x16x32_bf16 v[76:79], v[212:215], v[220:223], v[76:79]
	v_mfma_f32_16x16x32_bf16 v[68:71], v[194:197], v[228:231], v[68:71]
	v_mfma_f32_16x16x32_bf16 v[60:63], v[212:215], v[228:231], v[60:63]
	v_mfma_f32_16x16x32_bf16 v[52:55], v[194:197], v[236:239], v[52:55]
	v_mfma_f32_16x16x32_bf16 v[44:47], v[212:215], v[236:239], v[44:47]
	v_mfma_f32_16x16x32_bf16 v[36:39], v[194:197], v[244:247], v[36:39]
	v_mfma_f32_16x16x32_bf16 v[28:31], v[212:215], v[244:247], v[28:31]
	s_setprio 0
	s_barrier
	s_add_i32 s69, s69, 2
	s_add_u32 s12, s12, 0x100
	s_addc_u32 s13, s13, 0
	s_add_u32 s67, s67, 0x100
	s_addc_u32 s68, s68, 0
	s_cmp_gt_u32 s69, 29
	s_cbranch_scc0 .LBB0_1580
	s_and_b64 vcc, exec, s[50:51]
	s_cbranch_vccz .LBB0_1583
	s_barrier

.LBB0_1699:
	s_add_i32 s72, s16, 2
	s_add_u32 s12, s8, 0x100
	s_addc_u32 s13, s9, 0
	s_add_i32 s73, 0, 0x10000
	s_cmp_eq_u32 s20, s16
	s_cselect_b32 s19, s53, s13
	s_cselect_b32 s18, s52, s12
	s_cselect_b32 s17, s55, s71
	s_cselect_b32 s16, s54, s21
	s_add_i32 s74, 0, 0x14000
	v_add_u32_e32 v72, s73, v188
	v_add_u32_e32 v182, s74, v188
	ds_read_b128 v[60:63], v72
	ds_read_b128 v[64:67], v72 offset:1024
	ds_read_b128 v[68:71], v72 offset:2048
	ds_read_b128 v[72:75], v72 offset:3072
	ds_read_b128 v[190:193], v182
	ds_read_b128 v[194:197], v182 offset:1024
	ds_read_b128 v[206:209], v182 offset:2048
	ds_read_b128 v[212:215], v182 offset:3072
	v_lshl_add_u64 v[182:183], s[8:9], 0, v[176:177]
	s_add_i32 m0, s31, 0xc000
	ds_read_b128 v[216:219], v189
	ds_read_b128 v[220:223], v189 offset:1024
	ds_read_b128 v[224:227], v189 offset:2048
	ds_read_b128 v[228:231], v189 offset:3072
	ds_read_b128 v[232:235], v189 offset:4096
	ds_read_b128 v[236:239], v189 offset:5120
	ds_read_b128 v[240:243], v189 offset:6144
	ds_read_b128 v[244:247], v189 offset:7168
	global_load_lds_dwordx4 v[182:183], off
	v_lshl_add_u64 v[182:183], s[8:9], 0, v[178:179]
	s_add_i32 m0, s31, 0xe000
	s_nop 0
	global_load_lds_dwordx4 v[182:183], off
	s_waitcnt vmcnt(8)
	s_waitcnt lgkmcnt(0)
	s_barrier
	s_setprio 1
	s_waitcnt lgkmcnt(0)
	v_mfma_f32_16x16x32_bf16 v[168:171], v[60:63], v[216:219], v[168:171]
	v_mfma_f32_16x16x32_bf16 v[164:167], v[68:71], v[216:219], v[164:167]
	v_mfma_f32_16x16x32_bf16 v[152:155], v[60:63], v[224:227], v[152:155]
	v_mfma_f32_16x16x32_bf16 v[148:151], v[68:71], v[224:227], v[148:151]
	v_mfma_f32_16x16x32_bf16 v[136:139], v[60:63], v[232:235], v[136:139]
	v_mfma_f32_16x16x32_bf16 v[132:135], v[68:71], v[232:235], v[132:135]
	v_mfma_f32_16x16x32_bf16 v[120:123], v[60:63], v[240:243], v[120:123]
	v_mfma_f32_16x16x32_bf16 v[116:119], v[68:71], v[240:243], v[116:119]
	v_mfma_f32_16x16x32_bf16 v[168:171], v[64:67], v[220:223], v[168:171]
	v_mfma_f32_16x16x32_bf16 v[164:167], v[72:75], v[220:223], v[164:167]
	v_mfma_f32_16x16x32_bf16 v[152:155], v[64:67], v[228:231], v[152:155]
	v_mfma_f32_16x16x32_bf16 v[148:151], v[72:75], v[228:231], v[148:151]
	v_mfma_f32_16x16x32_bf16 v[136:139], v[64:67], v[236:239], v[136:139]
	v_mfma_f32_16x16x32_bf16 v[132:135], v[72:75], v[236:239], v[132:135]
	v_mfma_f32_16x16x32_bf16 v[120:123], v[64:67], v[244:247], v[120:123]
	v_mfma_f32_16x16x32_bf16 v[116:119], v[72:75], v[244:247], v[116:119]
	v_mfma_f32_16x16x32_bf16 v[160:163], v[190:193], v[216:219], v[160:163]
	v_mfma_f32_16x16x32_bf16 v[156:159], v[206:209], v[216:219], v[156:159]
	v_mfma_f32_16x16x32_bf16 v[144:147], v[190:193], v[224:227], v[144:147]
	v_mfma_f32_16x16x32_bf16 v[140:143], v[206:209], v[224:227], v[140:143]
	v_mfma_f32_16x16x32_bf16 v[128:131], v[190:193], v[232:235], v[128:131]
	v_mfma_f32_16x16x32_bf16 v[124:127], v[206:209], v[232:235], v[124:127]
	v_mfma_f32_16x16x32_bf16 v[112:115], v[190:193], v[240:243], v[112:115]
	v_mfma_f32_16x16x32_bf16 v[108:111], v[206:209], v[240:243], v[108:111]
	v_mfma_f32_16x16x32_bf16 v[160:163], v[194:197], v[220:223], v[160:163]
	v_mfma_f32_16x16x32_bf16 v[156:159], v[212:215], v[220:223], v[156:159]
	v_mfma_f32_16x16x32_bf16 v[144:147], v[194:197], v[228:231], v[144:147]
	v_mfma_f32_16x16x32_bf16 v[140:143], v[212:215], v[228:231], v[140:143]
	v_mfma_f32_16x16x32_bf16 v[128:131], v[194:197], v[236:239], v[128:131]
	v_mfma_f32_16x16x32_bf16 v[124:127], v[212:215], v[236:239], v[124:127]
	v_mfma_f32_16x16x32_bf16 v[112:115], v[194:197], v[244:247], v[112:115]
	v_mfma_f32_16x16x32_bf16 v[108:111], v[212:215], v[244:247], v[108:111]
	s_setprio 0
	s_barrier
	s_add_i32 s8, s73, s30
	v_lshl_add_u64 v[182:183], s[16:17], 0, v[2:3]
	s_mov_b32 m0, s8
	ds_read_b128 v[216:219], v189 offset:16384
	ds_read_b128 v[220:223], v189 offset:17408
	ds_read_b128 v[224:227], v189 offset:18432
	ds_read_b128 v[228:231], v189 offset:19456
	ds_read_b128 v[232:235], v189 offset:20480
	ds_read_b128 v[236:239], v189 offset:21504
	ds_read_b128 v[240:243], v189 offset:22528
	ds_read_b128 v[244:247], v189 offset:23552
	global_load_lds_dwordx4 v[182:183], off
	s_add_i32 m0, s8, 0x2000
	s_add_u32 s8, s16, 0x160000
	v_lshl_add_u64 v[200:201], s[16:17], 0, v[174:175]
	s_addc_u32 s9, s17, 0
	s_add_i32 s73, s74, s30
	global_load_lds_dwordx4 v[200:201], off
	v_lshl_add_u64 v[204:205], s[8:9], 0, v[2:3]
	s_mov_b32 m0, s73
	v_lshl_add_u64 v[248:249], s[18:19], 0, v[172:173]
	global_load_lds_dwordx4 v[204:205], off
	v_lshl_add_u64 v[204:205], s[8:9], 0, v[174:175]
	s_add_i32 m0, s73, 0x2000
	s_nop 0
	global_load_lds_dwordx4 v[204:205], off
	v_lshl_add_u64 v[204:205], s[18:19], 0, v[0:1]
	s_mov_b32 m0, s31
	s_nop 0
	global_load_lds_dwordx4 v[204:205], off
	s_mov_b32 m0, s34
	s_nop 0
	global_load_lds_dwordx4 v[248:249], off
	s_waitcnt vmcnt(8)
	s_waitcnt lgkmcnt(0)
	s_barrier
	s_setprio 1
	s_waitcnt lgkmcnt(0)
	v_mfma_f32_16x16x32_bf16 v[104:107], v[60:63], v[216:219], v[104:107]
	v_mfma_f32_16x16x32_bf16 v[100:103], v[68:71], v[216:219], v[100:103]
	v_mfma_f32_16x16x32_bf16 v[88:91], v[60:63], v[224:227], v[88:91]
	v_mfma_f32_16x16x32_bf16 v[84:87], v[68:71], v[224:227], v[84:87]
	v_mfma_f32_16x16x32_bf16 v[56:59], v[60:63], v[232:235], v[56:59]
	v_mfma_f32_16x16x32_bf16 v[52:55], v[68:71], v[232:235], v[52:55]
	v_mfma_f32_16x16x32_bf16 v[40:43], v[60:63], v[240:243], v[40:43]
	v_mfma_f32_16x16x32_bf16 v[36:39], v[68:71], v[240:243], v[36:39]
	v_mfma_f32_16x16x32_bf16 v[104:107], v[64:67], v[220:223], v[104:107]
	v_mfma_f32_16x16x32_bf16 v[100:103], v[72:75], v[220:223], v[100:103]
	v_mfma_f32_16x16x32_bf16 v[88:91], v[64:67], v[228:231], v[88:91]
	v_mfma_f32_16x16x32_bf16 v[84:87], v[72:75], v[228:231], v[84:87]
	v_mfma_f32_16x16x32_bf16 v[56:59], v[64:67], v[236:239], v[56:59]
	v_mfma_f32_16x16x32_bf16 v[52:55], v[72:75], v[236:239], v[52:55]
	v_mfma_f32_16x16x32_bf16 v[40:43], v[64:67], v[244:247], v[40:43]
	v_mfma_f32_16x16x32_bf16 v[36:39], v[72:75], v[244:247], v[36:39]
	v_mfma_f32_16x16x32_bf16 v[48:51], v[190:193], v[232:235], v[48:51]
	v_mfma_f32_16x16x32_bf16 v[44:47], v[206:209], v[232:235], v[44:47]
	v_mfma_f32_16x16x32_bf16 v[32:35], v[190:193], v[240:243], v[32:35]
	v_mfma_f32_16x16x32_bf16 v[28:31], v[206:209], v[240:243], v[28:31]
	v_mfma_f32_16x16x32_bf16 v[60:63], v[190:193], v[216:219], v[96:99]
	v_mfma_f32_16x16x32_bf16 v[64:67], v[206:209], v[216:219], v[92:95]
	v_mfma_f32_16x16x32_bf16 v[68:71], v[190:193], v[224:227], v[80:83]
	v_mfma_f32_16x16x32_bf16 v[72:75], v[206:209], v[224:227], v[76:79]
	v_mfma_f32_16x16x32_bf16 v[48:51], v[194:197], v[236:239], v[48:51]
	v_mfma_f32_16x16x32_bf16 v[44:47], v[212:215], v[236:239], v[44:47]
	v_mfma_f32_16x16x32_bf16 v[32:35], v[194:197], v[244:247], v[32:35]
	v_mfma_f32_16x16x32_bf16 v[28:31], v[212:215], v[244:247], v[28:31]
	v_mfma_f32_16x16x32_bf16 v[60:63], v[194:197], v[220:223], v[60:63]
	v_mfma_f32_16x16x32_bf16 v[64:67], v[212:215], v[220:223], v[64:67]
	v_mfma_f32_16x16x32_bf16 v[68:71], v[194:197], v[228:231], v[68:71]
	v_mfma_f32_16x16x32_bf16 v[72:75], v[212:215], v[228:231], v[72:75]
	s_setprio 0
	s_barrier
	s_add_i32 s73, 0, 0x18000
	s_add_i32 s74, 0, 0x1c000
	v_add_u32_e32 v96, s73, v188
	v_add_u32_e32 v212, s74, v188
	ds_read_b128 v[76:79], v96
	ds_read_b128 v[80:83], v96 offset:1024
	ds_read_b128 v[92:95], v96 offset:2048
	ds_read_b128 v[96:99], v96 offset:3072
	ds_read_b128 v[190:193], v212
	ds_read_b128 v[194:197], v212 offset:1024
	ds_read_b128 v[206:209], v212 offset:2048
	ds_read_b128 v[212:215], v212 offset:3072
	s_add_u32 s8, s18, 0x160000
	s_addc_u32 s9, s19, 0
	s_mov_b32 m0, s35
	v_lshl_add_u64 v[250:251], s[8:9], 0, v[0:1]
	ds_read_b128 v[216:219], v189 offset:32768
	ds_read_b128 v[220:223], v189 offset:33792
	ds_read_b128 v[224:227], v189 offset:34816
	ds_read_b128 v[228:231], v189 offset:35840
	ds_read_b128 v[232:235], v189 offset:36864
	ds_read_b128 v[236:239], v189 offset:37888
	ds_read_b128 v[240:243], v189 offset:38912
	ds_read_b128 v[244:247], v189 offset:39936
	global_load_lds_dwordx4 v[250:251], off
	v_lshl_add_u64 v[250:251], s[8:9], 0, v[172:173]
	s_mov_b32 m0, s36
	s_nop 0
	global_load_lds_dwordx4 v[250:251], off
	s_waitcnt vmcnt(8)
	s_waitcnt lgkmcnt(0)
	s_barrier
	s_setprio 1
	s_waitcnt lgkmcnt(0)
	v_mfma_f32_16x16x32_bf16 v[168:171], v[76:79], v[216:219], v[168:171]
	v_mfma_f32_16x16x32_bf16 v[164:167], v[92:95], v[216:219], v[164:167]
	v_mfma_f32_16x16x32_bf16 v[152:155], v[76:79], v[224:227], v[152:155]
	v_mfma_f32_16x16x32_bf16 v[148:151], v[92:95], v[224:227], v[148:151]
	v_mfma_f32_16x16x32_bf16 v[136:139], v[76:79], v[232:235], v[136:139]
	v_mfma_f32_16x16x32_bf16 v[132:135], v[92:95], v[232:235], v[132:135]
	v_mfma_f32_16x16x32_bf16 v[120:123], v[76:79], v[240:243], v[120:123]
	v_mfma_f32_16x16x32_bf16 v[116:119], v[92:95], v[240:243], v[116:119]
	v_mfma_f32_16x16x32_bf16 v[168:171], v[80:83], v[220:223], v[168:171]
	v_mfma_f32_16x16x32_bf16 v[164:167], v[96:99], v[220:223], v[164:167]
	v_mfma_f32_16x16x32_bf16 v[152:155], v[80:83], v[228:231], v[152:155]
	v_mfma_f32_16x16x32_bf16 v[148:151], v[96:99], v[228:231], v[148:151]
	v_mfma_f32_16x16x32_bf16 v[136:139], v[80:83], v[236:239], v[136:139]
	v_mfma_f32_16x16x32_bf16 v[132:135], v[96:99], v[236:239], v[132:135]
	v_mfma_f32_16x16x32_bf16 v[120:123], v[80:83], v[244:247], v[120:123]
	v_mfma_f32_16x16x32_bf16 v[116:119], v[96:99], v[244:247], v[116:119]
	v_mfma_f32_16x16x32_bf16 v[160:163], v[190:193], v[216:219], v[160:163]
	v_mfma_f32_16x16x32_bf16 v[156:159], v[206:209], v[216:219], v[156:159]
	v_mfma_f32_16x16x32_bf16 v[144:147], v[190:193], v[224:227], v[144:147]
	v_mfma_f32_16x16x32_bf16 v[140:143], v[206:209], v[224:227], v[140:143]
	v_mfma_f32_16x16x32_bf16 v[128:131], v[190:193], v[232:235], v[128:131]
	v_mfma_f32_16x16x32_bf16 v[124:127], v[206:209], v[232:235], v[124:127]
	v_mfma_f32_16x16x32_bf16 v[112:115], v[190:193], v[240:243], v[112:115]
	v_mfma_f32_16x16x32_bf16 v[108:111], v[206:209], v[240:243], v[108:111]
	v_mfma_f32_16x16x32_bf16 v[160:163], v[194:197], v[220:223], v[160:163]
	v_mfma_f32_16x16x32_bf16 v[156:159], v[212:215], v[220:223], v[156:159]
	v_mfma_f32_16x16x32_bf16 v[144:147], v[194:197], v[228:231], v[144:147]
	v_mfma_f32_16x16x32_bf16 v[140:143], v[212:215], v[228:231], v[140:143]
	v_mfma_f32_16x16x32_bf16 v[128:131], v[194:197], v[236:239], v[128:131]
	v_mfma_f32_16x16x32_bf16 v[124:127], v[212:215], v[236:239], v[124:127]
	v_mfma_f32_16x16x32_bf16 v[112:115], v[194:197], v[244:247], v[112:115]
	v_mfma_f32_16x16x32_bf16 v[108:111], v[212:215], v[244:247], v[108:111]
	s_setprio 0
	s_barrier
	s_add_i32 s8, s73, s30
	v_lshl_add_u64 v[182:183], v[182:183], 0, s[10:11]
	s_mov_b32 m0, s8
	ds_read_b128 v[216:219], v189 offset:49152
	ds_read_b128 v[220:223], v189 offset:50176
	ds_read_b128 v[224:227], v189 offset:51200
	ds_read_b128 v[228:231], v189 offset:52224
	ds_read_b128 v[232:235], v189 offset:53248
	ds_read_b128 v[236:239], v189 offset:54272
	ds_read_b128 v[240:243], v189 offset:55296
	ds_read_b128 v[244:247], v189 offset:56320
	global_load_lds_dwordx4 v[182:183], off
	s_add_i32 m0, s8, 0x2000
	s_add_u32 s8, s16, 0x160080
	v_lshl_add_u64 v[182:183], v[200:201], 0, s[10:11]
	s_addc_u32 s9, s17, 0
	s_add_i32 s16, s74, s30
	global_load_lds_dwordx4 v[182:183], off
	v_lshl_add_u64 v[182:183], s[8:9], 0, v[2:3]
	s_mov_b32 m0, s16
	s_nop 0
	global_load_lds_dwordx4 v[182:183], off
	v_lshl_add_u64 v[182:183], s[8:9], 0, v[174:175]
	s_add_i32 m0, s16, 0x2000
	s_nop 0
	global_load_lds_dwordx4 v[182:183], off
	v_lshl_add_u64 v[182:183], v[204:205], 0, s[10:11]
	s_mov_b32 m0, s60
	s_nop 0
	global_load_lds_dwordx4 v[182:183], off
	v_lshl_add_u64 v[182:183], v[248:249], 0, s[10:11]
	s_mov_b32 m0, s61
	s_nop 0
	global_load_lds_dwordx4 v[182:183], off
	s_waitcnt vmcnt(8)
	s_waitcnt lgkmcnt(0)
	s_barrier
	s_setprio 1
	s_waitcnt lgkmcnt(0)
	v_mfma_f32_16x16x32_bf16 v[104:107], v[76:79], v[216:219], v[104:107]
	v_mfma_f32_16x16x32_bf16 v[100:103], v[92:95], v[216:219], v[100:103]
	v_mfma_f32_16x16x32_bf16 v[88:91], v[76:79], v[224:227], v[88:91]
	v_mfma_f32_16x16x32_bf16 v[84:87], v[92:95], v[224:227], v[84:87]
	v_mfma_f32_16x16x32_bf16 v[56:59], v[76:79], v[232:235], v[56:59]
	v_mfma_f32_16x16x32_bf16 v[52:55], v[92:95], v[232:235], v[52:55]
	v_mfma_f32_16x16x32_bf16 v[40:43], v[76:79], v[240:243], v[40:43]
	v_mfma_f32_16x16x32_bf16 v[36:39], v[92:95], v[240:243], v[36:39]
	v_mfma_f32_16x16x32_bf16 v[104:107], v[80:83], v[220:223], v[104:107]
	v_mfma_f32_16x16x32_bf16 v[100:103], v[96:99], v[220:223], v[100:103]
	v_mfma_f32_16x16x32_bf16 v[88:91], v[80:83], v[228:231], v[88:91]
	v_mfma_f32_16x16x32_bf16 v[84:87], v[96:99], v[228:231], v[84:87]
	v_mfma_f32_16x16x32_bf16 v[56:59], v[80:83], v[236:239], v[56:59]
	v_mfma_f32_16x16x32_bf16 v[52:55], v[96:99], v[236:239], v[52:55]
	v_mfma_f32_16x16x32_bf16 v[40:43], v[80:83], v[244:247], v[40:43]
	v_mfma_f32_16x16x32_bf16 v[36:39], v[96:99], v[244:247], v[36:39]
	v_mfma_f32_16x16x32_bf16 v[60:63], v[190:193], v[216:219], v[60:63]
	v_mfma_f32_16x16x32_bf16 v[96:99], v[194:197], v[220:223], v[60:63]
	v_mfma_f32_16x16x32_bf16 v[60:63], v[206:209], v[216:219], v[64:67]
	v_mfma_f32_16x16x32_bf16 v[92:95], v[212:215], v[220:223], v[60:63]
	v_mfma_f32_16x16x32_bf16 v[60:63], v[190:193], v[224:227], v[68:71]
	v_mfma_f32_16x16x32_bf16 v[80:83], v[194:197], v[228:231], v[60:63]
	v_mfma_f32_16x16x32_bf16 v[60:63], v[206:209], v[224:227], v[72:75]
	v_mfma_f32_16x16x32_bf16 v[48:51], v[190:193], v[232:235], v[48:51]
	v_mfma_f32_16x16x32_bf16 v[44:47], v[206:209], v[232:235], v[44:47]
	v_mfma_f32_16x16x32_bf16 v[32:35], v[190:193], v[240:243], v[32:35]
	v_mfma_f32_16x16x32_bf16 v[28:31], v[206:209], v[240:243], v[28:31]
	v_mfma_f32_16x16x32_bf16 v[76:79], v[212:215], v[228:231], v[60:63]
	v_mfma_f32_16x16x32_bf16 v[48:51], v[194:197], v[236:239], v[48:51]
	v_mfma_f32_16x16x32_bf16 v[44:47], v[212:215], v[236:239], v[44:47]
	v_mfma_f32_16x16x32_bf16 v[32:35], v[194:197], v[244:247], v[32:35]
	v_mfma_f32_16x16x32_bf16 v[28:31], v[212:215], v[244:247], v[28:31]
	s_setprio 0
	s_barrier
	s_add_u32 s21, s21, 0x100
	s_addc_u32 s71, s71, 0
	s_cmp_ge_u32 s72, s70
	s_mov_b64 s[8:9], s[12:13]
	s_mov_b32 s16, s72
	s_cbranch_scc0 .LBB0_1699
	s_and_b64 vcc, exec, s[50:51]
	s_cbranch_vccz .LBB0_1702
	s_barrier
